# P2 tile header: the conservative vmcnt(0) before the accumulator zeroing removed (all rope-table loads are waited inside their path)
# baseline (speedup 1.0000x reference)
; template <class Epi, class Sched, bool ALIGN_EPI = false, bool SP2 = false>
; __device__ __forceinline__ void gemm_phase(PG8_LAS unsigned char* lds, const Gemm g, const Sched& S, const Epi& E) {
;     ...
;         const bool has_next = S.next(ui + 1, nxt);
;         const char* nA = has_next ? (const char*)g.A + (size_t)nxt.pm * tstepA + (size_t)((nxt.pn >> g.a_shift) * g.a_stride) : cA; const char* nB = has_next ? (const char*)g.Bt + (size_t)nxt.pn * tstepB : cB;
;     ...
;         if (!has_next) break;
; #pragma unroll
;         for (int a = 0; a < 2; ++a)
; #pragma unroll
;             for (int b = 0; b < 2; ++b)
; #pragma unroll
;                 for (int m = 0; m < 4; ++m)
; #pragma unroll
;                     for (int n = 0; n < 2; ++n) acc[a][b][m][n] = (f32x4){0.f, 0.f, 0.f, 0.f};
;         cur = nxt; cA = nA; cB = nB; ++ui;
.LBB0_364:
	s_ashr_i32 s21, s20, 31
	s_lshl_b64 s[10:11], s[20:21], 21
	s_add_u32 s22, s54, s10
	s_addc_u32 s23, s55, s11
	s_and_b64 s[10:11], s[6:7], exec
	s_cselect_b32 s9, s23, s61
	s_cselect_b32 s10, s22, s60
	s_ashr_i32 s19, s18, 31
	s_lshl_b64 s[24:25], s[18:19], 21
	s_add_u32 s56, s88, s24
	s_addc_u32 s57, s89, s25
	s_and_b64 s[24:25], s[6:7], exec
	s_cselect_b32 s11, s57, s67
	s_cselect_b32 s19, s56, s66
	s_add_u32 s60, s60, 0x100080
	s_addc_u32 s61, s61, 0
	s_add_u32 s21, s66, 0x100
	v_mov_b32_e32 v2, 0
	s_addc_u32 s72, s67, 0
	s_mov_b32 s73, -2
	v_mov_b32_e32 v3, v2
	v_mov_b64_e32 v[4:5], 0
	v_mov_b64_e32 v[6:7], 0
	v_mov_b64_e32 v[8:9], 0
	s_nop 0
	v_mov_b64_e32 v[18:19], 0
	v_mov_b64_e32 v[20:21], 0
	v_mov_b64_e32 v[22:23], 0
	v_mov_b64_e32 v[24:25], 0
	v_mov_b64_e32 v[34:35], 0
	v_mov_b64_e32 v[36:37], 0
	v_mov_b64_e32 v[38:39], 0
	v_mov_b64_e32 v[40:41], 0
	v_mov_b64_e32 v[50:51], 0
	v_mov_b64_e32 v[52:53], 0
	v_mov_b64_e32 v[54:55], 0
	v_mov_b64_e32 v[56:57], 0
	v_mov_b64_e32 v[10:11], 0
	v_mov_b64_e32 v[12:13], 0
	v_mov_b64_e32 v[14:15], 0
	v_mov_b64_e32 v[16:17], 0
	v_mov_b64_e32 v[26:27], 0
	v_mov_b64_e32 v[28:29], 0
	v_mov_b64_e32 v[30:31], 0
	v_mov_b64_e32 v[32:33], 0
	v_mov_b64_e32 v[42:43], 0
	v_mov_b64_e32 v[44:45], 0
	v_mov_b64_e32 v[46:47], 0
	v_mov_b64_e32 v[48:49], 0
	v_mov_b64_e32 v[58:59], 0
	v_mov_b64_e32 v[60:61], 0
	v_mov_b64_e32 v[62:63], 0
	v_mov_b64_e32 v[64:65], 0
	v_mov_b64_e32 v[66:67], 0
	v_mov_b64_e32 v[68:69], 0
	v_mov_b64_e32 v[70:71], 0
	v_mov_b64_e32 v[72:73], 0
	v_mov_b64_e32 v[82:83], 0
	v_mov_b64_e32 v[84:85], 0
	v_mov_b64_e32 v[86:87], 0
	v_mov_b64_e32 v[88:89], 0
	v_mov_b64_e32 v[98:99], 0
	v_mov_b64_e32 v[100:101], 0
	v_mov_b64_e32 v[102:103], 0
	v_mov_b64_e32 v[104:105], 0
	v_mov_b64_e32 v[114:115], 0
	v_mov_b64_e32 v[116:117], 0
	v_mov_b64_e32 v[118:119], 0
	v_mov_b64_e32 v[120:121], 0
	v_mov_b64_e32 v[74:75], 0
	v_mov_b64_e32 v[76:77], 0
	v_mov_b64_e32 v[78:79], 0
	v_mov_b64_e32 v[80:81], 0
	v_mov_b64_e32 v[90:91], 0
	v_mov_b64_e32 v[92:93], 0
	v_mov_b64_e32 v[94:95], 0
	v_mov_b64_e32 v[96:97], 0
	v_mov_b64_e32 v[106:107], 0
	v_mov_b64_e32 v[108:109], 0
	v_mov_b64_e32 v[110:111], 0
	v_mov_b64_e32 v[112:113], 0
	v_mov_b64_e32 v[122:123], 0
	v_mov_b64_e32 v[124:125], 0
	v_mov_b64_e32 v[126:127], 0
	v_mov_b64_e32 v[128:129], 0
	s_setprio 1
	s_cmp_eq_u64 s[16:17], 0
	s_cbranch_scc1 .Lsp_LBB0_365
	s_setprio 0
